# phase 15: workgroup takes the 8 query heads of a kv group consecutively, K/V staged into LDS once per group instead of per head
# speedup vs baseline: 1.0202x; 1.0167x over previous
.LBB0_762:
	s_or_b64 exec, exec, s[4:5]
	s_cmpk_gt_i32 s2, 0x1ff
	s_waitcnt lgkmcnt(0)
	s_barrier
	s_cbranch_scc1 .LBB0_781
	s_waitcnt vmcnt(4)
	v_mbcnt_hi_u32_b32 v89, -1, v207
	v_and_b32_e32 v0, 64, v89
	s_lshl_b32 s38, s2, 6
	s_add_i32 s39, s92, -1
	s_lshl_b32 s39, s39, 3
	s_mov_b32 s17, 0
	v_mov_b32_e32 v81, 0
	s_movk_i32 s40, 0xa00
	s_movk_i32 s41, 0x1070
	s_movk_i32 s50, 0x90
	v_mov_b64_e32 v[82:83], s[44:45]
	s_movk_i32 s51, 0x7f
	v_mov_b32_e32 v88, 0xff800000
	s_movk_i32 s52, 0x7e
	v_xor_b32_e32 v90, 32, v89
	v_add_u32_e32 v91, 64, v0
	s_lshl_b32 s53, s2, 3
	s_branch .LBB0_765
.LBB0_764:
	s_or_b64 exec, exec, s[4:5]
	v_ashrrev_i32_e32 v124, 6, v85
	v_mad_u64_u32 v[10:11], s[4:5], v8, s50, v[12:13]
	v_and_b32_e32 v96, 31, v85
	v_lshlrev_b32_e32 v125, 5, v124
	s_or_b32 s4, s8, s7
	v_or_b32_e32 v97, v125, v96
	s_and_b32 s9, s53, 15
	s_mov_b64 vcc, s[100:101]
	s_cbranch_vccz .Lp15_sk0
	s_waitcnt vmcnt(1)
	ds_write_b128 v10, v[4:7]
.Lp15_sk0:
	v_lshl_add_u32 v4, v8, 1, v13
	v_add_u32_e32 v84, s4, v97
	s_mov_b64 vcc, s[100:101]
	s_cbranch_vccz .Lp15_sk1
	s_waitcnt vmcnt(0)
	ds_write_b16 v4, v0 offset:36864
	ds_write_b16_d16_hi v4, v0 offset:37392
	ds_write_b16 v4, v1 offset:37920
	ds_write_b16_d16_hi v4, v1 offset:38448
	ds_write_b16 v4, v2 offset:38976
	ds_write_b16_d16_hi v4, v2 offset:39504
	ds_write_b16 v4, v3 offset:40032
	ds_write_b16_d16_hi v4, v3 offset:40560
.Lp15_sk1:
	v_bfe_u32 v80, v85, 5, 1
	v_mad_i64_i32 v[0:1], s[4:5], v84, s40, v[82:83]
	s_lshl_b32 s16, s9, 7
	v_lshl_add_u64 v[0:1], v[0:1], 0, s[16:17]
	v_lshlrev_b32_e32 v86, 4, v80
	v_mov_b32_e32 v87, v81
	v_lshl_add_u64 v[114:115], v[0:1], 0, v[86:87]
	s_waitcnt lgkmcnt(0)
	s_barrier
	global_load_dwordx4 v[0:3], v[114:115], off
	global_load_dwordx4 v[102:105], v[114:115], off offset:32
	v_mad_u64_u32 v[92:93], s[4:5], v97, s50, v[86:87]
	ds_read_b128 v[4:7], v92
	ds_read_b128 v[8:11], v92 offset:32
	v_add_u32_e32 v95, 1, v124
	v_lshlrev_b32_e32 v126, 5, v95
	v_or_b32_e32 v12, v126, v96
	v_mad_u64_u32 v[118:119], s[4:5], v12, s50, v[86:87]
	v_add_u32_e32 v94, 2, v124
	v_lshlrev_b32_e32 v127, 5, v94
	v_or_b32_e32 v12, v127, v96
	v_mad_u64_u32 v[120:121], s[4:5], v12, s50, v[86:87]
	v_add_u32_e32 v93, 3, v124
	v_lshlrev_b32_e32 v128, 5, v93
	v_or_b32_e32 v16, v128, v96
	v_mad_u64_u32 v[122:123], s[4:5], v16, s50, v[86:87]
	s_lshl_b32 s4, s9, 2
	s_cmp_lg_u32 s6, 0
	s_cselect_b64 s[18:19], -1, 0
	s_add_i32 s53, s53, 1
	s_add_i32 s38, s38, 8
	s_and_b32 s99, s53, 7
	s_cbranch_scc1 .Lp15_same
	s_add_i32 s53, s53, s39
	s_lshl_b32 s99, s39, 3
	s_add_i32 s38, s38, s99
.Lp15_same:
	s_waitcnt vmcnt(1) lgkmcnt(1)
	v_mfma_f32_32x32x16_bf16 v[64:79], v[4:7], v[0:3], 0
	ds_read_b128 v[4:7], v118
	ds_read_b128 v[12:15], v118 offset:32
	ds_read_b128 v[98:101], v120 offset:32
	s_waitcnt lgkmcnt(2)
	v_mfma_f32_32x32x16_bf16 v[48:63], v[4:7], v[0:3], 0
	ds_read_b128 v[4:7], v120
	s_waitcnt lgkmcnt(0)
	v_mfma_f32_32x32x16_bf16 v[32:47], v[4:7], v[0:3], 0
	ds_read_b128 v[4:7], v122
	ds_read_b128 v[106:109], v122 offset:32
	global_load_dwordx4 v[110:113], v[114:115], off offset:64
	s_nop 0
	global_load_dwordx4 v[114:117], v[114:115], off offset:96
	s_waitcnt lgkmcnt(1)
	v_mfma_f32_32x32x16_bf16 v[16:31], v[4:7], v[0:3], 0
	v_mov_b32_e32 v4, s4
	global_load_dword v87, v4, s[62:63]
	s_waitcnt vmcnt(3)
	v_mfma_f32_32x32x16_bf16 v[64:79], v[8:11], v[102:105], v[64:79]
	ds_read_b128 v[4:7], v92 offset:64
	ds_read_b128 v[8:11], v92 offset:96
	v_add_u32_e32 v92, 4, v124
	v_mfma_f32_32x32x16_bf16 v[48:63], v[12:15], v[102:105], v[48:63]
	v_mfma_f32_32x32x16_bf16 v[32:47], v[98:101], v[102:105], v[32:47]
	v_lshlrev_b32_e32 v100, 2, v80
	v_lshlrev_b32_e32 v101, 5, v92
	v_or_b32_e32 v129, v100, v125
	v_add_u32_e32 v98, 0x80, v97
	v_cmp_lt_i32_e64 s[8:9], s52, v129
	v_cmp_gt_u32_e32 vcc, v100, v96
	v_cmp_lt_i32_e64 s[6:7], s51, v129
	s_waitcnt lgkmcnt(2)
	v_mfma_f32_32x32x16_bf16 v[16:31], v[106:109], v[102:105], v[16:31]
	s_or_b64 s[56:57], s[18:19], s[8:9]
	v_cmp_ge_u32_e64 s[4:5], v100, v96
	s_or_b64 s[54:55], s[18:19], s[6:7]
	v_cmp_lt_i32_e64 s[6:7], v129, v98
	s_and_b64 s[4:5], s[4:5], s[6:7]
	v_lshlrev_b32_e32 v80, 3, v80
	s_waitcnt vmcnt(2) lgkmcnt(1)
	v_mfma_f32_32x32x16_bf16 v[64:79], v[4:7], v[110:113], v[64:79]
	ds_read_b128 v[4:7], v118 offset:64
	ds_read_b128 v[12:15], v118 offset:96
	ds_read_b128 v[106:109], v120 offset:96
	s_waitcnt lgkmcnt(2)
	v_mfma_f32_32x32x16_bf16 v[48:63], v[4:7], v[110:113], v[48:63]
	ds_read_b128 v[4:7], v120 offset:64
	s_waitcnt vmcnt(1)
	v_mfma_f32_32x32x16_bf16 v[64:79], v[8:11], v[114:117], v[64:79]
	s_waitcnt lgkmcnt(0)
	v_mfma_f32_32x32x16_bf16 v[32:47], v[4:7], v[110:113], v[32:47]
	v_or_b32_e32 v4, v101, v96
	v_or_b32_e32 v5, 2, v129
	s_waitcnt vmcnt(0)
	v_mad_u64_u32 v[124:125], s[10:11], v4, s50, v[86:87]
	v_cmp_le_i32_e64 s[10:11], v129, v98
	v_cmp_gt_i32_e64 s[8:9], v5, v97
	v_cmp_le_i32_e64 s[12:13], v5, v98
	v_cmp_lt_i32_e64 s[14:15], s51, v5
	ds_read_b128 v[4:7], v122 offset:64
	ds_read_b128 v[8:11], v122 offset:96
	s_and_b64 s[10:11], vcc, s[10:11]
	s_and_b64 vcc, s[10:11], s[54:55]
	s_and_b64 s[6:7], s[8:9], s[12:13]
	s_or_b64 s[8:9], s[18:19], s[14:15]
	v_cndmask_b32_e32 v99, v88, v64, vcc
	s_and_b64 vcc, s[4:5], s[56:57]
	s_waitcnt lgkmcnt(1)
	v_mfma_f32_32x32x16_bf16 v[16:31], v[4:7], v[110:113], v[16:31]
	v_cndmask_b32_e32 v65, v88, v65, vcc
	s_and_b64 vcc, s[6:7], s[8:9]
	v_or_b32_e32 v5, 3, v129
	v_cndmask_b32_e32 v64, v88, v66, vcc
	v_cmp_gt_i32_e32 vcc, v5, v97
	v_cmp_le_i32_e64 s[4:5], v5, v98
	s_and_b64 s[4:5], vcc, s[4:5]
	v_cmp_lt_i32_e32 vcc, s51, v5
	s_or_b64 s[6:7], s[18:19], vcc
	s_and_b64 vcc, s[4:5], s[6:7]
	v_cndmask_b32_e32 v66, v88, v67, vcc
	v_or_b32_e32 v67, 8, v129
	v_cmp_gt_i32_e32 vcc, v67, v97
	v_cmp_le_i32_e64 s[4:5], v67, v98
	s_and_b64 s[4:5], vcc, s[4:5]
	v_cmp_lt_i32_e32 vcc, s51, v67
	s_or_b64 s[6:7], s[18:19], vcc
	s_and_b64 vcc, s[4:5], s[6:7]
	v_cndmask_b32_e32 v67, v88, v68, vcc
	v_or_b32_e32 v68, 9, v129
	v_cmp_gt_i32_e32 vcc, v68, v97
	v_cmp_le_i32_e64 s[4:5], v68, v98
	s_and_b64 s[4:5], vcc, s[4:5]
	v_cmp_lt_i32_e32 vcc, s51, v68
	s_or_b64 s[6:7], s[18:19], vcc
	s_and_b64 vcc, s[4:5], s[6:7]
	v_cndmask_b32_e32 v68, v88, v69, vcc
	v_or_b32_e32 v69, 10, v129
	v_cmp_gt_i32_e32 vcc, v69, v97
	v_cmp_le_i32_e64 s[4:5], v69, v98
	s_and_b64 s[4:5], vcc, s[4:5]
	v_cmp_lt_i32_e32 vcc, s51, v69
	s_or_b64 s[6:7], s[18:19], vcc
	s_and_b64 vcc, s[4:5], s[6:7]
	v_cndmask_b32_e32 v69, v88, v70, vcc
	v_or_b32_e32 v70, 11, v129
	v_cmp_gt_i32_e32 vcc, v70, v97
	v_cmp_le_i32_e64 s[4:5], v70, v98
	s_and_b64 s[4:5], vcc, s[4:5]
	v_cmp_lt_i32_e32 vcc, s51, v70
	s_or_b64 s[6:7], s[18:19], vcc
	s_and_b64 vcc, s[4:5], s[6:7]
	v_cndmask_b32_e32 v70, v88, v71, vcc
	v_or_b32_e32 v71, 16, v129
	v_cmp_gt_i32_e32 vcc, v71, v97
	v_cmp_le_i32_e64 s[4:5], v71, v98
	s_and_b64 s[4:5], vcc, s[4:5]
	v_cmp_lt_i32_e32 vcc, s51, v71
	s_or_b64 s[6:7], s[18:19], vcc
	s_and_b64 vcc, s[4:5], s[6:7]
	v_cndmask_b32_e32 v71, v88, v72, vcc
	v_or_b32_e32 v72, 17, v129
	v_cmp_gt_i32_e32 vcc, v72, v97
	v_cmp_le_i32_e64 s[4:5], v72, v98
	s_and_b64 s[4:5], vcc, s[4:5]
	v_cmp_lt_i32_e32 vcc, s51, v72
	s_or_b64 s[6:7], s[18:19], vcc
	s_and_b64 vcc, s[4:5], s[6:7]
	v_cndmask_b32_e32 v72, v88, v73, vcc
	v_or_b32_e32 v73, 18, v129
	v_cmp_gt_i32_e32 vcc, v73, v97
	v_cmp_le_i32_e64 s[4:5], v73, v98
	s_and_b64 s[4:5], vcc, s[4:5]
	v_cmp_lt_i32_e32 vcc, s51, v73
	s_or_b64 s[6:7], s[18:19], vcc
	s_and_b64 vcc, s[4:5], s[6:7]
	v_cndmask_b32_e32 v73, v88, v74, vcc
	v_or_b32_e32 v74, 19, v129
	v_cmp_gt_i32_e32 vcc, v74, v97
	v_cmp_le_i32_e64 s[4:5], v74, v98
	s_and_b64 s[4:5], vcc, s[4:5]
	v_cmp_lt_i32_e32 vcc, s51, v74
	s_or_b64 s[6:7], s[18:19], vcc
	s_and_b64 vcc, s[4:5], s[6:7]
	v_cndmask_b32_e32 v74, v88, v75, vcc
	v_or_b32_e32 v75, 24, v129
	v_cmp_gt_i32_e32 vcc, v75, v97
	v_cmp_le_i32_e64 s[4:5], v75, v98
	s_and_b64 s[4:5], vcc, s[4:5]
	v_cmp_lt_i32_e32 vcc, s51, v75
	s_or_b64 s[6:7], s[18:19], vcc
	s_and_b64 vcc, s[4:5], s[6:7]
	v_cndmask_b32_e32 v75, v88, v76, vcc
	v_or_b32_e32 v76, 25, v129
	v_mfma_f32_32x32x16_bf16 v[48:63], v[12:15], v[114:117], v[48:63]
	v_cmp_gt_i32_e32 vcc, v76, v97
	v_cmp_le_i32_e64 s[4:5], v76, v98
	v_max3_f32 v4, v87, v99, v65
	s_and_b64 s[4:5], vcc, s[4:5]
	v_cmp_lt_i32_e32 vcc, s51, v76
	v_max3_f32 v130, v4, v64, v66
	s_or_b64 s[6:7], s[18:19], vcc
	v_mfma_f32_32x32x16_bf16 v[32:47], v[106:109], v[114:117], v[32:47]
	ds_read_b128 v[12:15], v124
	ds_read_b128 v[106:109], v124 offset:32
	ds_read_b128 v[118:121], v124 offset:64
	ds_read_b128 v[122:125], v124 offset:96
	s_and_b64 vcc, s[4:5], s[6:7]
	v_cndmask_b32_e32 v76, v88, v77, vcc
	v_or_b32_e32 v77, 26, v129
	v_cmp_gt_i32_e32 vcc, v77, v97
	v_cmp_le_i32_e64 s[4:5], v77, v98
	s_and_b64 s[4:5], vcc, s[4:5]
	s_waitcnt lgkmcnt(4)
	v_mfma_f32_32x32x16_bf16 v[16:31], v[8:11], v[114:117], v[16:31]
	v_cmp_lt_i32_e32 vcc, s51, v77
	s_or_b64 s[6:7], s[18:19], vcc
	s_and_b64 vcc, s[4:5], s[6:7]
	v_cndmask_b32_e32 v77, v88, v78, vcc
	v_or_b32_e32 v78, 27, v129
	v_cmp_gt_i32_e32 vcc, v78, v97
	v_cmp_le_i32_e64 s[4:5], v78, v98
	s_waitcnt lgkmcnt(3)
	v_mfma_f32_32x32x16_bf16 v[0:15], v[12:15], v[0:3], 0
	s_and_b64 s[4:5], vcc, s[4:5]
	v_cmp_lt_i32_e32 vcc, s51, v78
	s_or_b64 s[6:7], s[18:19], vcc
	s_and_b64 vcc, s[4:5], s[6:7]
	v_cndmask_b32_e32 v78, v88, v79, vcc
	v_sub_u32_e32 v86, v86, v80
	s_waitcnt lgkmcnt(2)
	v_mfma_f32_32x32x16_bf16 v[0:15], v[106:109], v[102:105], v[0:15]
	v_max3_f32 v102, v130, v67, v68
	v_max3_f32 v102, v102, v69, v70
	v_max3_f32 v102, v102, v71, v72
	v_max3_f32 v102, v102, v73, v74
	v_max3_f32 v102, v102, v75, v76
	v_max3_f32 v79, v102, v77, v78
	v_or_b32_e32 v102, v100, v126
	v_cmp_gt_i32_e32 vcc, v102, v97
	v_cmp_le_i32_e64 s[4:5], v102, v98
	s_and_b64 s[4:5], vcc, s[4:5]
	v_cmp_lt_i32_e32 vcc, s51, v102
	s_or_b64 s[6:7], s[18:19], vcc
	s_and_b64 vcc, s[4:5], s[6:7]
	v_cndmask_b32_e32 v48, v88, v48, vcc
	v_cmp_ge_i32_e32 vcc, v102, v97
	v_cmp_lt_i32_e64 s[4:5], v102, v98
	s_and_b64 s[4:5], vcc, s[4:5]
	v_cmp_lt_i32_e32 vcc, s52, v102
	s_or_b64 s[6:7], s[18:19], vcc
	s_and_b64 vcc, s[4:5], s[6:7]
	v_or_b32_e32 v103, 2, v102
	v_cndmask_b32_e32 v49, v88, v49, vcc
	v_cmp_gt_i32_e32 vcc, v103, v97
	v_cmp_le_i32_e64 s[4:5], v103, v98
	s_and_b64 s[4:5], vcc, s[4:5]
	v_cmp_lt_i32_e32 vcc, s51, v103
	s_or_b64 s[6:7], s[18:19], vcc
	s_and_b64 vcc, s[4:5], s[6:7]
	v_or_b32_e32 v103, 3, v102
	v_cndmask_b32_e32 v50, v88, v50, vcc
	v_cmp_gt_i32_e32 vcc, v103, v97
	v_cmp_le_i32_e64 s[4:5], v103, v98
	s_and_b64 s[4:5], vcc, s[4:5]
	v_cmp_lt_i32_e32 vcc, s51, v103
	s_or_b64 s[6:7], s[18:19], vcc
	s_and_b64 vcc, s[4:5], s[6:7]
	v_or_b32_e32 v103, 8, v102
	v_cndmask_b32_e32 v51, v88, v51, vcc
	v_cmp_gt_i32_e32 vcc, v103, v97
	v_cmp_le_i32_e64 s[4:5], v103, v98
	s_and_b64 s[4:5], vcc, s[4:5]
	v_cmp_lt_i32_e32 vcc, s51, v103
	s_or_b64 s[6:7], s[18:19], vcc
	s_and_b64 vcc, s[4:5], s[6:7]
	v_or_b32_e32 v103, 9, v102
	v_cndmask_b32_e32 v52, v88, v52, vcc
	v_cmp_gt_i32_e32 vcc, v103, v97
	v_cmp_le_i32_e64 s[4:5], v103, v98
	s_and_b64 s[4:5], vcc, s[4:5]
	v_cmp_lt_i32_e32 vcc, s51, v103
	s_or_b64 s[6:7], s[18:19], vcc
	s_and_b64 vcc, s[4:5], s[6:7]
	v_or_b32_e32 v103, 10, v102
	v_cndmask_b32_e32 v53, v88, v53, vcc
	v_cmp_gt_i32_e32 vcc, v103, v97
	v_cmp_le_i32_e64 s[4:5], v103, v98
	s_and_b64 s[4:5], vcc, s[4:5]
	v_cmp_lt_i32_e32 vcc, s51, v103
	s_or_b64 s[6:7], s[18:19], vcc
	s_and_b64 vcc, s[4:5], s[6:7]
	v_or_b32_e32 v103, 11, v102
	v_cndmask_b32_e32 v54, v88, v54, vcc
	v_cmp_gt_i32_e32 vcc, v103, v97
	v_cmp_le_i32_e64 s[4:5], v103, v98
	s_and_b64 s[4:5], vcc, s[4:5]
	v_cmp_lt_i32_e32 vcc, s51, v103
	s_or_b64 s[6:7], s[18:19], vcc
	s_and_b64 vcc, s[4:5], s[6:7]
	v_or_b32_e32 v103, 16, v102
	v_cndmask_b32_e32 v55, v88, v55, vcc
	v_cmp_gt_i32_e32 vcc, v103, v97
	v_cmp_le_i32_e64 s[4:5], v103, v98
	s_and_b64 s[4:5], vcc, s[4:5]
	v_cmp_lt_i32_e32 vcc, s51, v103
	s_or_b64 s[6:7], s[18:19], vcc
	s_and_b64 vcc, s[4:5], s[6:7]
	v_or_b32_e32 v103, 17, v102
	v_cndmask_b32_e32 v56, v88, v56, vcc
	v_cmp_gt_i32_e32 vcc, v103, v97
	v_cmp_le_i32_e64 s[4:5], v103, v98
	s_and_b64 s[4:5], vcc, s[4:5]
	v_cmp_lt_i32_e32 vcc, s51, v103
	s_or_b64 s[6:7], s[18:19], vcc
	s_and_b64 vcc, s[4:5], s[6:7]
	v_or_b32_e32 v103, 18, v102
	v_cndmask_b32_e32 v57, v88, v57, vcc
	v_cmp_gt_i32_e32 vcc, v103, v97
	v_cmp_le_i32_e64 s[4:5], v103, v98
	s_and_b64 s[4:5], vcc, s[4:5]
	v_cmp_lt_i32_e32 vcc, s51, v103
	s_or_b64 s[6:7], s[18:19], vcc
	s_and_b64 vcc, s[4:5], s[6:7]
	v_or_b32_e32 v103, 19, v102
	v_cndmask_b32_e32 v58, v88, v58, vcc
	v_cmp_gt_i32_e32 vcc, v103, v97
	v_cmp_le_i32_e64 s[4:5], v103, v98
	s_and_b64 s[4:5], vcc, s[4:5]
	v_cmp_lt_i32_e32 vcc, s51, v103
	s_or_b64 s[6:7], s[18:19], vcc
	s_and_b64 vcc, s[4:5], s[6:7]
	v_or_b32_e32 v103, 24, v102
	v_cndmask_b32_e32 v59, v88, v59, vcc
	v_cmp_gt_i32_e32 vcc, v103, v97
	v_cmp_le_i32_e64 s[4:5], v103, v98
	s_and_b64 s[4:5], vcc, s[4:5]
	v_cmp_lt_i32_e32 vcc, s51, v103
	s_or_b64 s[6:7], s[18:19], vcc
	s_and_b64 vcc, s[4:5], s[6:7]
	v_or_b32_e32 v103, 25, v102
	v_cndmask_b32_e32 v60, v88, v60, vcc
	v_cmp_gt_i32_e32 vcc, v103, v97
	v_cmp_le_i32_e64 s[4:5], v103, v98
	s_and_b64 s[4:5], vcc, s[4:5]
	v_cmp_lt_i32_e32 vcc, s51, v103
	s_or_b64 s[6:7], s[18:19], vcc
	s_and_b64 vcc, s[4:5], s[6:7]
	v_or_b32_e32 v103, 26, v102
	v_cndmask_b32_e32 v61, v88, v61, vcc
	v_cmp_gt_i32_e32 vcc, v103, v97
	v_cmp_le_i32_e64 s[4:5], v103, v98
	s_and_b64 s[4:5], vcc, s[4:5]
	v_cmp_lt_i32_e32 vcc, s51, v103
	s_or_b64 s[6:7], s[18:19], vcc
	s_and_b64 vcc, s[4:5], s[6:7]
	v_or_b32_e32 v102, 27, v102
	v_cndmask_b32_e32 v62, v88, v62, vcc
	v_cmp_gt_i32_e32 vcc, v102, v97
	v_cmp_le_i32_e64 s[4:5], v102, v98
	v_max3_f32 v79, v79, v48, v49
	s_and_b64 s[4:5], vcc, s[4:5]
	v_cmp_lt_i32_e32 vcc, s51, v102
	v_max3_f32 v79, v79, v50, v51
	s_or_b64 s[6:7], s[18:19], vcc
	s_waitcnt lgkmcnt(1)
	v_mfma_f32_32x32x16_bf16 v[0:15], v[118:121], v[110:113], v[0:15]
	v_max3_f32 v79, v79, v52, v53
	s_and_b64 vcc, s[4:5], s[6:7]
	v_or_b32_e32 v113, v100, v127
	v_max3_f32 v79, v79, v54, v55
	v_cndmask_b32_e32 v63, v88, v63, vcc
	v_cmp_gt_i32_e32 vcc, v113, v97
	v_cmp_le_i32_e64 s[4:5], v113, v98
	v_max3_f32 v79, v79, v56, v57
	s_and_b64 s[4:5], vcc, s[4:5]
	v_cmp_lt_i32_e32 vcc, s51, v113
	v_max3_f32 v79, v79, v58, v59
	s_or_b64 s[6:7], s[18:19], vcc
	v_max3_f32 v79, v79, v60, v61
	s_and_b64 vcc, s[4:5], s[6:7]
	v_max3_f32 v103, v79, v62, v63
	v_cndmask_b32_e32 v79, v88, v32, vcc
	v_cmp_ge_i32_e32 vcc, v113, v97
	v_cmp_lt_i32_e64 s[4:5], v113, v98
	s_and_b64 s[4:5], vcc, s[4:5]
	v_cmp_lt_i32_e32 vcc, s52, v113
	s_or_b64 s[6:7], s[18:19], vcc
	s_and_b64 vcc, s[4:5], s[6:7]
	v_cndmask_b32_e32 v102, v88, v33, vcc
	v_or_b32_e32 v33, 2, v113
	v_cmp_gt_i32_e32 vcc, v33, v97
	v_cmp_le_i32_e64 s[4:5], v33, v98
	s_and_b64 s[4:5], vcc, s[4:5]
	v_cmp_lt_i32_e32 vcc, s51, v33
	s_or_b64 s[6:7], s[18:19], vcc
	s_and_b64 vcc, s[4:5], s[6:7]
	v_or_b32_e32 v33, 3, v113
	v_max3_f32 v32, v103, v79, v102
	v_cndmask_b32_e32 v103, v88, v34, vcc
	v_cmp_gt_i32_e32 vcc, v33, v97
	v_cmp_le_i32_e64 s[4:5], v33, v98
	s_and_b64 s[4:5], vcc, s[4:5]
	v_cmp_lt_i32_e32 vcc, s51, v33
	s_or_b64 s[6:7], s[18:19], vcc
	s_and_b64 vcc, s[4:5], s[6:7]
	v_or_b32_e32 v33, 8, v113
	v_cndmask_b32_e32 v104, v88, v35, vcc
	v_cmp_gt_i32_e32 vcc, v33, v97
	v_cmp_le_i32_e64 s[4:5], v33, v98
	s_and_b64 s[4:5], vcc, s[4:5]
	v_cmp_lt_i32_e32 vcc, s51, v33
	s_or_b64 s[6:7], s[18:19], vcc
	s_and_b64 vcc, s[4:5], s[6:7]
	v_or_b32_e32 v33, 9, v113
	v_cndmask_b32_e32 v105, v88, v36, vcc
	v_cmp_gt_i32_e32 vcc, v33, v97
	v_cmp_le_i32_e64 s[4:5], v33, v98
	s_and_b64 s[4:5], vcc, s[4:5]
	v_cmp_lt_i32_e32 vcc, s51, v33
	s_or_b64 s[6:7], s[18:19], vcc
	s_and_b64 vcc, s[4:5], s[6:7]
	v_or_b32_e32 v33, 10, v113
	v_cndmask_b32_e32 v106, v88, v37, vcc
	v_cmp_gt_i32_e32 vcc, v33, v97
	v_cmp_le_i32_e64 s[4:5], v33, v98
	s_and_b64 s[4:5], vcc, s[4:5]
	v_cmp_lt_i32_e32 vcc, s51, v33
	s_or_b64 s[6:7], s[18:19], vcc
	s_and_b64 vcc, s[4:5], s[6:7]
	v_or_b32_e32 v33, 11, v113
	v_cndmask_b32_e32 v107, v88, v38, vcc
	v_cmp_gt_i32_e32 vcc, v33, v97
	v_cmp_le_i32_e64 s[4:5], v33, v98
	s_and_b64 s[4:5], vcc, s[4:5]
	v_cmp_lt_i32_e32 vcc, s51, v33
	s_or_b64 s[6:7], s[18:19], vcc
	s_and_b64 vcc, s[4:5], s[6:7]
	v_or_b32_e32 v33, 16, v113
	v_cndmask_b32_e32 v108, v88, v39, vcc
	v_cmp_gt_i32_e32 vcc, v33, v97
	v_cmp_le_i32_e64 s[4:5], v33, v98
	s_and_b64 s[4:5], vcc, s[4:5]
	v_cmp_lt_i32_e32 vcc, s51, v33
	s_or_b64 s[6:7], s[18:19], vcc
	s_and_b64 vcc, s[4:5], s[6:7]
	v_or_b32_e32 v33, 17, v113
	v_cndmask_b32_e32 v109, v88, v40, vcc
	v_cmp_gt_i32_e32 vcc, v33, v97
	v_cmp_le_i32_e64 s[4:5], v33, v98
	s_and_b64 s[4:5], vcc, s[4:5]
	v_cmp_lt_i32_e32 vcc, s51, v33
	s_or_b64 s[6:7], s[18:19], vcc
	s_and_b64 vcc, s[4:5], s[6:7]
	v_or_b32_e32 v33, 18, v113
	v_cndmask_b32_e32 v110, v88, v41, vcc
	v_cmp_gt_i32_e32 vcc, v33, v97
	v_cmp_le_i32_e64 s[4:5], v33, v98
	s_and_b64 s[4:5], vcc, s[4:5]
	v_cmp_lt_i32_e32 vcc, s51, v33
	s_or_b64 s[6:7], s[18:19], vcc
	s_and_b64 vcc, s[4:5], s[6:7]
	v_or_b32_e32 v33, 19, v113
	v_cndmask_b32_e32 v111, v88, v42, vcc
	v_cmp_gt_i32_e32 vcc, v33, v97
	v_cmp_le_i32_e64 s[4:5], v33, v98
	s_and_b64 s[4:5], vcc, s[4:5]
	v_cmp_lt_i32_e32 vcc, s51, v33
	s_or_b64 s[6:7], s[18:19], vcc
	s_and_b64 vcc, s[4:5], s[6:7]
	v_or_b32_e32 v33, 24, v113
	v_cndmask_b32_e32 v112, v88, v43, vcc
	v_cmp_gt_i32_e32 vcc, v33, v97
	v_cmp_le_i32_e64 s[4:5], v33, v98
	s_and_b64 s[4:5], vcc, s[4:5]
	v_cmp_lt_i32_e32 vcc, s51, v33
	s_or_b64 s[6:7], s[18:19], vcc
	s_and_b64 vcc, s[4:5], s[6:7]
	v_or_b32_e32 v33, 25, v113
	s_waitcnt lgkmcnt(0)
	v_mfma_f32_32x32x16_bf16 v[0:15], v[122:125], v[114:117], v[0:15]
	v_cndmask_b32_e32 v114, v88, v44, vcc
	v_cmp_gt_i32_e32 vcc, v33, v97
	v_cmp_le_i32_e64 s[4:5], v33, v98
	s_and_b64 s[4:5], vcc, s[4:5]
	v_cmp_lt_i32_e32 vcc, s51, v33
	s_or_b64 s[6:7], s[18:19], vcc
	s_and_b64 vcc, s[4:5], s[6:7]
	v_or_b32_e32 v33, 26, v113
	v_cndmask_b32_e32 v45, v88, v45, vcc
	v_cmp_gt_i32_e32 vcc, v33, v97
	v_cmp_le_i32_e64 s[4:5], v33, v98
	s_and_b64 s[4:5], vcc, s[4:5]
	v_cmp_lt_i32_e32 vcc, s51, v33
	s_or_b64 s[6:7], s[18:19], vcc
	s_and_b64 vcc, s[4:5], s[6:7]
	v_or_b32_e32 v33, 27, v113
	v_cndmask_b32_e32 v46, v88, v46, vcc
	v_cmp_gt_i32_e32 vcc, v33, v97
	v_cmp_le_i32_e64 s[4:5], v33, v98
	s_and_b64 s[4:5], vcc, s[4:5]
	v_cmp_lt_i32_e32 vcc, s51, v33
	s_or_b64 s[6:7], s[18:19], vcc
	s_and_b64 vcc, s[4:5], s[6:7]
	v_or_b32_e32 v33, v100, v128
	v_cndmask_b32_e32 v47, v88, v47, vcc
	v_cmp_gt_i32_e32 vcc, v33, v97
	v_cmp_le_i32_e64 s[4:5], v33, v98
	s_and_b64 s[4:5], vcc, s[4:5]
	v_cmp_lt_i32_e32 vcc, s51, v33
	s_or_b64 s[6:7], s[18:19], vcc
	s_and_b64 vcc, s[4:5], s[6:7]
	v_cndmask_b32_e32 v16, v88, v16, vcc
	v_cmp_ge_i32_e32 vcc, v33, v97
	v_cmp_lt_i32_e64 s[4:5], v33, v98
	s_and_b64 s[4:5], vcc, s[4:5]
	v_cmp_lt_i32_e32 vcc, s52, v33
	s_or_b64 s[6:7], s[18:19], vcc
	s_and_b64 vcc, s[4:5], s[6:7]
	v_or_b32_e32 v34, 2, v33
	v_cndmask_b32_e32 v17, v88, v17, vcc
	v_cmp_gt_i32_e32 vcc, v34, v97
	v_cmp_le_i32_e64 s[4:5], v34, v98
	s_and_b64 s[4:5], vcc, s[4:5]
	v_cmp_lt_i32_e32 vcc, s51, v34
	s_or_b64 s[6:7], s[18:19], vcc
	s_and_b64 vcc, s[4:5], s[6:7]
	v_or_b32_e32 v34, 3, v33
	v_cndmask_b32_e32 v18, v88, v18, vcc
	v_cmp_gt_i32_e32 vcc, v34, v97
	v_cmp_le_i32_e64 s[4:5], v34, v98
	s_and_b64 s[4:5], vcc, s[4:5]
	v_cmp_lt_i32_e32 vcc, s51, v34
	s_or_b64 s[6:7], s[18:19], vcc
	s_and_b64 vcc, s[4:5], s[6:7]
	v_or_b32_e32 v34, 8, v33
	v_cndmask_b32_e32 v19, v88, v19, vcc
	v_cmp_gt_i32_e32 vcc, v34, v97
	v_cmp_le_i32_e64 s[4:5], v34, v98
	s_and_b64 s[4:5], vcc, s[4:5]
	v_cmp_lt_i32_e32 vcc, s51, v34
	s_or_b64 s[6:7], s[18:19], vcc
	s_and_b64 vcc, s[4:5], s[6:7]
	v_or_b32_e32 v34, 9, v33
	v_cndmask_b32_e32 v20, v88, v20, vcc
	v_cmp_gt_i32_e32 vcc, v34, v97
	v_cmp_le_i32_e64 s[4:5], v34, v98
	s_and_b64 s[4:5], vcc, s[4:5]
	v_cmp_lt_i32_e32 vcc, s51, v34
	s_or_b64 s[6:7], s[18:19], vcc
	s_and_b64 vcc, s[4:5], s[6:7]
	v_or_b32_e32 v34, 10, v33
	v_cndmask_b32_e32 v21, v88, v21, vcc
	v_cmp_gt_i32_e32 vcc, v34, v97
	v_cmp_le_i32_e64 s[4:5], v34, v98
	s_and_b64 s[4:5], vcc, s[4:5]
	v_cmp_lt_i32_e32 vcc, s51, v34
	s_or_b64 s[6:7], s[18:19], vcc
	s_and_b64 vcc, s[4:5], s[6:7]
	v_or_b32_e32 v34, 11, v33
	v_cndmask_b32_e32 v22, v88, v22, vcc
	v_cmp_gt_i32_e32 vcc, v34, v97
	v_cmp_le_i32_e64 s[4:5], v34, v98
	s_and_b64 s[4:5], vcc, s[4:5]
	v_cmp_lt_i32_e32 vcc, s51, v34
	s_or_b64 s[6:7], s[18:19], vcc
	s_and_b64 vcc, s[4:5], s[6:7]
	v_or_b32_e32 v34, 16, v33
	v_cndmask_b32_e32 v23, v88, v23, vcc
	v_cmp_gt_i32_e32 vcc, v34, v97
	v_cmp_le_i32_e64 s[4:5], v34, v98
	s_and_b64 s[4:5], vcc, s[4:5]
	v_cmp_lt_i32_e32 vcc, s51, v34
	s_or_b64 s[6:7], s[18:19], vcc
	s_and_b64 vcc, s[4:5], s[6:7]
	v_or_b32_e32 v34, 17, v33
	v_cndmask_b32_e32 v24, v88, v24, vcc
	v_cmp_gt_i32_e32 vcc, v34, v97
	v_cmp_le_i32_e64 s[4:5], v34, v98
	s_and_b64 s[4:5], vcc, s[4:5]
	v_cmp_lt_i32_e32 vcc, s51, v34
	s_or_b64 s[6:7], s[18:19], vcc
	s_and_b64 vcc, s[4:5], s[6:7]
	v_or_b32_e32 v34, 18, v33
	v_cndmask_b32_e32 v25, v88, v25, vcc
	v_cmp_gt_i32_e32 vcc, v34, v97
	v_cmp_le_i32_e64 s[4:5], v34, v98
	s_and_b64 s[4:5], vcc, s[4:5]
	v_cmp_lt_i32_e32 vcc, s51, v34
	s_or_b64 s[6:7], s[18:19], vcc
	s_and_b64 vcc, s[4:5], s[6:7]
	v_or_b32_e32 v34, 19, v33
	v_cndmask_b32_e32 v26, v88, v26, vcc
	v_cmp_gt_i32_e32 vcc, v34, v97
	v_cmp_le_i32_e64 s[4:5], v34, v98
	s_and_b64 s[4:5], vcc, s[4:5]
	v_cmp_lt_i32_e32 vcc, s51, v34
	s_or_b64 s[6:7], s[18:19], vcc
	s_and_b64 vcc, s[4:5], s[6:7]
	v_or_b32_e32 v34, 24, v33
	v_cndmask_b32_e32 v27, v88, v27, vcc
	v_cmp_gt_i32_e32 vcc, v34, v97
	v_cmp_le_i32_e64 s[4:5], v34, v98
	s_and_b64 s[4:5], vcc, s[4:5]
	v_cmp_lt_i32_e32 vcc, s51, v34
	s_or_b64 s[6:7], s[18:19], vcc
	s_and_b64 vcc, s[4:5], s[6:7]
	v_or_b32_e32 v34, 25, v33
	v_cndmask_b32_e32 v28, v88, v28, vcc
	v_cmp_gt_i32_e32 vcc, v34, v97
	v_cmp_le_i32_e64 s[4:5], v34, v98
	s_and_b64 s[4:5], vcc, s[4:5]
	v_cmp_lt_i32_e32 vcc, s51, v34
	s_or_b64 s[6:7], s[18:19], vcc
	s_and_b64 vcc, s[4:5], s[6:7]
	v_or_b32_e32 v34, 26, v33
	v_cndmask_b32_e32 v29, v88, v29, vcc
	v_cmp_gt_i32_e32 vcc, v34, v97
	v_cmp_le_i32_e64 s[4:5], v34, v98
	s_and_b64 s[4:5], vcc, s[4:5]
	v_cmp_lt_i32_e32 vcc, s51, v34
	s_or_b64 s[6:7], s[18:19], vcc
	s_and_b64 vcc, s[4:5], s[6:7]
	v_or_b32_e32 v33, 27, v33
	v_cndmask_b32_e32 v30, v88, v30, vcc
	v_cmp_gt_i32_e32 vcc, v33, v97
	v_cmp_le_i32_e64 s[4:5], v33, v98
	s_and_b64 s[4:5], vcc, s[4:5]
	v_cmp_lt_i32_e32 vcc, s51, v33
	s_or_b64 s[6:7], s[18:19], vcc
	s_and_b64 vcc, s[4:5], s[6:7]
	v_or_b32_e32 v33, v100, v101
	v_cndmask_b32_e32 v31, v88, v31, vcc
	v_cmp_gt_i32_e32 vcc, v33, v97
	v_cmp_le_i32_e64 s[4:5], v33, v98
	v_max3_f32 v32, v32, v103, v104
	s_and_b64 s[4:5], vcc, s[4:5]
	v_cmp_lt_i32_e32 vcc, s51, v33
	v_max3_f32 v32, v32, v105, v106
	s_or_b64 s[6:7], s[18:19], vcc
	v_max3_f32 v32, v32, v107, v108
	s_and_b64 vcc, s[4:5], s[6:7]
	v_max3_f32 v32, v32, v109, v110
	v_cndmask_b32_e32 v100, v88, v0, vcc
	v_cmp_ge_i32_e32 vcc, v33, v97
	v_cmp_lt_i32_e64 s[4:5], v33, v98
	v_max3_f32 v32, v32, v111, v112
	s_and_b64 s[4:5], vcc, s[4:5]
	v_cmp_lt_i32_e32 vcc, s52, v33
	v_max3_f32 v32, v32, v114, v45
	s_or_b64 s[6:7], s[18:19], vcc
	v_max3_f32 v32, v32, v46, v47
	s_and_b64 vcc, s[4:5], s[6:7]
	v_or_b32_e32 v0, 2, v33
	v_max3_f32 v32, v32, v16, v17
	v_cndmask_b32_e32 v1, v88, v1, vcc
	v_cmp_gt_i32_e32 vcc, v0, v97
	v_cmp_le_i32_e64 s[4:5], v0, v98
	v_max3_f32 v32, v32, v18, v19
	s_and_b64 s[4:5], vcc, s[4:5]
	v_cmp_lt_i32_e32 vcc, s51, v0
	v_max3_f32 v32, v32, v20, v21
	s_or_b64 s[6:7], s[18:19], vcc
	v_max3_f32 v32, v32, v22, v23
	s_and_b64 vcc, s[4:5], s[6:7]
	v_or_b32_e32 v0, 3, v33
	v_max3_f32 v32, v32, v24, v25
	v_cndmask_b32_e32 v2, v88, v2, vcc
	v_cmp_gt_i32_e32 vcc, v0, v97
	v_cmp_le_i32_e64 s[4:5], v0, v98
	v_max3_f32 v32, v32, v26, v27
	s_and_b64 s[4:5], vcc, s[4:5]
	v_cmp_lt_i32_e32 vcc, s51, v0
	v_max3_f32 v32, v32, v28, v29
	s_or_b64 s[6:7], s[18:19], vcc
	v_max3_f32 v32, v32, v30, v31
	s_and_b64 vcc, s[4:5], s[6:7]
	v_max3_f32 v32, v32, v100, v1
	v_cndmask_b32_e32 v0, v88, v3, vcc
	v_max3_f32 v3, v32, v2, v0
	v_or_b32_e32 v32, 8, v33
	v_cmp_gt_i32_e32 vcc, v32, v97
	v_cmp_le_i32_e64 s[4:5], v32, v98
	s_and_b64 s[4:5], vcc, s[4:5]
	v_cmp_lt_i32_e32 vcc, s51, v32
	s_or_b64 s[6:7], s[18:19], vcc
	s_and_b64 vcc, s[4:5], s[6:7]
	v_cndmask_b32_e32 v101, v88, v4, vcc
	v_or_b32_e32 v4, 9, v33
	v_cmp_gt_i32_e32 vcc, v4, v97
	v_cmp_le_i32_e64 s[4:5], v4, v98
	s_and_b64 s[4:5], vcc, s[4:5]
	v_cmp_lt_i32_e32 vcc, s51, v4
	s_or_b64 s[6:7], s[18:19], vcc
	s_and_b64 vcc, s[4:5], s[6:7]
	v_or_b32_e32 v4, 10, v33
	v_cndmask_b32_e32 v44, v88, v5, vcc
	v_cmp_gt_i32_e32 vcc, v4, v97
	v_cmp_le_i32_e64 s[4:5], v4, v98
	s_and_b64 s[4:5], vcc, s[4:5]
	v_cmp_lt_i32_e32 vcc, s51, v4
	s_or_b64 s[6:7], s[18:19], vcc
	s_and_b64 vcc, s[4:5], s[6:7]
	v_or_b32_e32 v4, 11, v33
	v_cndmask_b32_e32 v42, v88, v6, vcc
	v_cmp_gt_i32_e32 vcc, v4, v97
	v_cmp_le_i32_e64 s[4:5], v4, v98
	s_and_b64 s[4:5], vcc, s[4:5]
	v_cmp_lt_i32_e32 vcc, s51, v4
	s_or_b64 s[6:7], s[18:19], vcc
	s_and_b64 vcc, s[4:5], s[6:7]
	v_or_b32_e32 v4, 16, v33
	v_cndmask_b32_e32 v43, v88, v7, vcc
	v_cmp_gt_i32_e32 vcc, v4, v97
	v_cmp_le_i32_e64 s[4:5], v4, v98
	s_and_b64 s[4:5], vcc, s[4:5]
	v_cmp_lt_i32_e32 vcc, s51, v4
	s_or_b64 s[6:7], s[18:19], vcc
	s_and_b64 vcc, s[4:5], s[6:7]
	v_or_b32_e32 v4, 17, v33
	v_cndmask_b32_e32 v41, v88, v8, vcc
	v_cmp_gt_i32_e32 vcc, v4, v97
	v_cmp_le_i32_e64 s[4:5], v4, v98
	s_and_b64 s[4:5], vcc, s[4:5]
	v_cmp_lt_i32_e32 vcc, s51, v4
	s_or_b64 s[6:7], s[18:19], vcc
	s_and_b64 vcc, s[4:5], s[6:7]
	v_or_b32_e32 v4, 18, v33
	v_cndmask_b32_e32 v39, v88, v9, vcc
	v_cmp_gt_i32_e32 vcc, v4, v97
	v_cmp_le_i32_e64 s[4:5], v4, v98
	s_and_b64 s[4:5], vcc, s[4:5]
	v_cmp_lt_i32_e32 vcc, s51, v4
	s_or_b64 s[6:7], s[18:19], vcc
	s_and_b64 vcc, s[4:5], s[6:7]
	v_or_b32_e32 v4, 19, v33
	v_cndmask_b32_e32 v40, v88, v10, vcc
	v_cmp_gt_i32_e32 vcc, v4, v97
	v_cmp_le_i32_e64 s[4:5], v4, v98
	s_and_b64 s[4:5], vcc, s[4:5]
	v_cmp_lt_i32_e32 vcc, s51, v4
	s_or_b64 s[6:7], s[18:19], vcc
	s_and_b64 vcc, s[4:5], s[6:7]
	v_or_b32_e32 v4, 24, v33
	v_cndmask_b32_e32 v38, v88, v11, vcc
	v_cmp_gt_i32_e32 vcc, v4, v97
	v_cmp_le_i32_e64 s[4:5], v4, v98
	s_and_b64 s[4:5], vcc, s[4:5]
	v_cmp_lt_i32_e32 vcc, s51, v4
	s_or_b64 s[6:7], s[18:19], vcc
	s_and_b64 vcc, s[4:5], s[6:7]
	v_or_b32_e32 v4, 25, v33
	v_cndmask_b32_e32 v35, v88, v12, vcc
	v_cmp_gt_i32_e32 vcc, v4, v97
	v_cmp_le_i32_e64 s[4:5], v4, v98
	s_and_b64 s[4:5], vcc, s[4:5]
	v_cmp_lt_i32_e32 vcc, s51, v4
	s_or_b64 s[6:7], s[18:19], vcc
	s_and_b64 vcc, s[4:5], s[6:7]
	v_or_b32_e32 v4, 26, v33
	v_cndmask_b32_e32 v37, v88, v13, vcc
	v_cmp_gt_i32_e32 vcc, v4, v97
	v_cmp_le_i32_e64 s[4:5], v4, v98
	s_and_b64 s[4:5], vcc, s[4:5]
	v_cmp_lt_i32_e32 vcc, s51, v4
	s_or_b64 s[6:7], s[18:19], vcc
	s_and_b64 vcc, s[4:5], s[6:7]
	v_or_b32_e32 v4, 27, v33
	v_cndmask_b32_e32 v36, v88, v14, vcc
	v_cmp_gt_i32_e32 vcc, v4, v97
	v_cmp_le_i32_e64 s[4:5], v4, v98
	v_max3_f32 v3, v3, v101, v44
	s_and_b64 s[4:5], vcc, s[4:5]
	v_cmp_lt_i32_e32 vcc, s51, v4
	v_max3_f32 v3, v3, v42, v43
	s_or_b64 s[6:7], s[18:19], vcc
	v_max3_f32 v3, v3, v41, v39
	s_and_b64 vcc, s[4:5], s[6:7]
	v_max3_f32 v3, v3, v40, v38
	v_cndmask_b32_e32 v34, v88, v15, vcc
	v_cmp_lt_i32_e32 vcc, v90, v91
	v_max3_f32 v3, v3, v35, v37
	v_max3_f32 v3, v3, v36, v34
	v_cndmask_b32_e32 v4, v89, v90, vcc
	v_lshlrev_b32_e32 v32, 2, v4
	ds_bpermute_b32 v4, v32, v3
	s_cmpk_lt_i32 s53, 0x1000
	s_waitcnt lgkmcnt(0)
	v_max_f32_e32 v4, v4, v4
	v_max_f32_e32 v33, v3, v4
	v_sub_f32_e32 v4, v65, v33
	v_mul_f32_e32 v4, 0x3fb8aa3b, v4
	v_exp_f32_e32 v7, v4
	v_sub_f32_e32 v4, v64, v33
	v_mul_f32_e32 v4, 0x3fb8aa3b, v4
	v_exp_f32_e32 v8, v4
	v_sub_f32_e32 v4, v66, v33
	v_mul_f32_e32 v4, 0x3fb8aa3b, v4
	v_exp_f32_e32 v9, v4
	v_sub_f32_e32 v4, v67, v33
	v_mul_f32_e32 v4, 0x3fb8aa3b, v4
	v_exp_f32_e32 v10, v4
	v_sub_f32_e32 v4, v68, v33
	v_mul_f32_e32 v4, 0x3fb8aa3b, v4
	v_exp_f32_e32 v11, v4
	v_sub_f32_e32 v4, v69, v33
	v_mul_f32_e32 v4, 0x3fb8aa3b, v4
	v_exp_f32_e32 v12, v4
	v_sub_f32_e32 v4, v70, v33
	v_mul_f32_e32 v4, 0x3fb8aa3b, v4
	v_exp_f32_e32 v13, v4
	v_sub_f32_e32 v4, v71, v33
	v_mul_f32_e32 v4, 0x3fb8aa3b, v4
	v_exp_f32_e32 v64, v4
	v_sub_f32_e32 v4, v72, v33
	v_mul_f32_e32 v4, 0x3fb8aa3b, v4
	v_exp_f32_e32 v65, v4
	v_sub_f32_e32 v4, v73, v33
	v_mul_f32_e32 v4, 0x3fb8aa3b, v4
	v_exp_f32_e32 v66, v4
	v_sub_f32_e32 v4, v74, v33
	v_mul_f32_e32 v4, 0x3fb8aa3b, v4
	v_exp_f32_e32 v67, v4
	v_sub_f32_e32 v4, v75, v33
	v_mul_f32_e32 v4, 0x3fb8aa3b, v4
	v_exp_f32_e32 v68, v4
	v_sub_f32_e32 v4, v76, v33
	v_mul_f32_e32 v4, 0x3fb8aa3b, v4
	v_exp_f32_e32 v69, v4
	v_sub_f32_e32 v4, v77, v33
	v_mul_f32_e32 v4, 0x3fb8aa3b, v4
	v_exp_f32_e32 v70, v4
	v_sub_f32_e32 v4, v78, v33
	v_mul_f32_e32 v4, 0x3fb8aa3b, v4
	v_exp_f32_e32 v71, v4
	v_sub_f32_e32 v4, v48, v33
	v_mul_f32_e32 v4, 0x3fb8aa3b, v4
	v_exp_f32_e32 v72, v4
	v_sub_f32_e32 v4, v49, v33
	v_mul_f32_e32 v4, 0x3fb8aa3b, v4
	v_exp_f32_e32 v73, v4
	v_sub_f32_e32 v4, v50, v33
	v_mul_f32_e32 v4, 0x3fb8aa3b, v4
	v_exp_f32_e32 v74, v4
	v_sub_f32_e32 v4, v51, v33
	v_mul_f32_e32 v4, 0x3fb8aa3b, v4
	v_exp_f32_e32 v75, v4
	v_sub_f32_e32 v4, v52, v33
	v_mul_f32_e32 v4, 0x3fb8aa3b, v4
	v_exp_f32_e32 v76, v4
	v_sub_f32_e32 v4, v53, v33
	v_mul_f32_e32 v4, 0x3fb8aa3b, v4
	v_exp_f32_e32 v77, v4
	v_sub_f32_e32 v4, v54, v33
	v_mul_f32_e32 v4, 0x3fb8aa3b, v4
	v_exp_f32_e32 v78, v4
	v_sub_f32_e32 v4, v55, v33
	v_mul_f32_e32 v4, 0x3fb8aa3b, v4
	v_exp_f32_e32 v97, v4
	v_sub_f32_e32 v4, v56, v33
	v_mul_f32_e32 v4, 0x3fb8aa3b, v4
	v_exp_f32_e32 v98, v4
	v_sub_f32_e32 v4, v57, v33
	v_mul_f32_e32 v4, 0x3fb8aa3b, v4
	v_sub_f32_e32 v3, v99, v33
	v_exp_f32_e32 v99, v4
	v_sub_f32_e32 v4, v58, v33
	v_mul_f32_e32 v4, 0x3fb8aa3b, v4
	v_exp_f32_e32 v58, v4
	v_sub_f32_e32 v4, v59, v33
	v_mul_f32_e32 v4, 0x3fb8aa3b, v4
	v_exp_f32_e32 v59, v4
	v_sub_f32_e32 v4, v60, v33
	v_mul_f32_e32 v4, 0x3fb8aa3b, v4
	v_exp_f32_e32 v60, v4
	v_sub_f32_e32 v4, v61, v33
	v_mul_f32_e32 v4, 0x3fb8aa3b, v4
	v_exp_f32_e32 v61, v4
	v_sub_f32_e32 v4, v62, v33
	v_mul_f32_e32 v4, 0x3fb8aa3b, v4
	v_exp_f32_e32 v62, v4
	v_sub_f32_e32 v4, v63, v33
	v_mul_f32_e32 v4, 0x3fb8aa3b, v4
	v_exp_f32_e32 v63, v4
	v_sub_f32_e32 v4, v79, v33
	v_mul_f32_e32 v3, 0x3fb8aa3b, v3
	v_mul_f32_e32 v4, 0x3fb8aa3b, v4
	v_exp_f32_e32 v6, v3
	v_exp_f32_e32 v79, v4
	v_sub_f32_e32 v4, v102, v33
	v_mul_f32_e32 v4, 0x3fb8aa3b, v4
	v_exp_f32_e32 v102, v4
	v_sub_f32_e32 v4, v103, v33
	v_mul_f32_e32 v4, 0x3fb8aa3b, v4
	v_add_f32_e32 v3, 0, v6
	v_exp_f32_e32 v103, v4
	v_sub_f32_e32 v4, v104, v33
	v_add_f32_e32 v3, v7, v3
	v_mul_f32_e32 v4, 0x3fb8aa3b, v4
	v_add_f32_e32 v3, v8, v3
	v_exp_f32_e32 v104, v4
	v_sub_f32_e32 v4, v105, v33
	v_add_f32_e32 v3, v9, v3
	v_mul_f32_e32 v4, 0x3fb8aa3b, v4
	v_add_f32_e32 v3, v10, v3
	v_exp_f32_e32 v105, v4
	v_sub_f32_e32 v4, v106, v33
	v_add_f32_e32 v3, v11, v3
	v_mul_f32_e32 v4, 0x3fb8aa3b, v4
	v_add_f32_e32 v3, v12, v3
	v_exp_f32_e32 v106, v4
	v_sub_f32_e32 v4, v107, v33
	v_add_f32_e32 v3, v13, v3
	v_mul_f32_e32 v4, 0x3fb8aa3b, v4
	v_add_f32_e32 v3, v64, v3
	v_exp_f32_e32 v107, v4
	v_sub_f32_e32 v4, v108, v33
	v_add_f32_e32 v3, v65, v3
	v_mul_f32_e32 v4, 0x3fb8aa3b, v4
	v_add_f32_e32 v3, v66, v3
	v_exp_f32_e32 v108, v4
	v_sub_f32_e32 v4, v109, v33
	v_add_f32_e32 v3, v67, v3
	v_mul_f32_e32 v4, 0x3fb8aa3b, v4
	v_add_f32_e32 v3, v68, v3
	v_exp_f32_e32 v109, v4
	v_sub_f32_e32 v4, v110, v33
	v_add_f32_e32 v3, v69, v3
	v_mul_f32_e32 v4, 0x3fb8aa3b, v4
	v_add_f32_e32 v3, v70, v3
	v_exp_f32_e32 v110, v4
	v_sub_f32_e32 v4, v111, v33
	v_add_f32_e32 v3, v71, v3
	v_mul_f32_e32 v4, 0x3fb8aa3b, v4
	v_add_f32_e32 v3, v72, v3
	v_exp_f32_e32 v111, v4
	v_sub_f32_e32 v4, v112, v33
	v_add_f32_e32 v3, v73, v3
	v_mul_f32_e32 v4, 0x3fb8aa3b, v4
	v_add_f32_e32 v3, v74, v3
	v_exp_f32_e32 v112, v4
	v_sub_f32_e32 v4, v114, v33
	v_add_f32_e32 v3, v75, v3
	v_mul_f32_e32 v4, 0x3fb8aa3b, v4
	v_add_f32_e32 v3, v76, v3
	v_exp_f32_e32 v113, v4
	v_sub_f32_e32 v4, v45, v33
	v_add_f32_e32 v3, v77, v3
	v_mul_f32_e32 v4, 0x3fb8aa3b, v4
	v_add_f32_e32 v3, v78, v3
	v_exp_f32_e32 v114, v4
	v_sub_f32_e32 v4, v46, v33
	v_add_f32_e32 v3, v97, v3
	v_mul_f32_e32 v4, 0x3fb8aa3b, v4
	v_add_f32_e32 v3, v98, v3
	v_exp_f32_e32 v115, v4
	v_sub_f32_e32 v4, v47, v33
	v_add_f32_e32 v3, v99, v3
	v_mul_f32_e32 v4, 0x3fb8aa3b, v4
	v_add_f32_e32 v3, v58, v3
	v_exp_f32_e32 v116, v4
	v_sub_f32_e32 v4, v16, v33
	v_add_f32_e32 v3, v59, v3
	v_mul_f32_e32 v4, 0x3fb8aa3b, v4
	v_add_f32_e32 v3, v60, v3
	v_exp_f32_e32 v117, v4
	v_sub_f32_e32 v4, v17, v33
	v_add_f32_e32 v3, v61, v3
	v_mul_f32_e32 v4, 0x3fb8aa3b, v4
	v_add_f32_e32 v3, v62, v3
	v_exp_f32_e32 v118, v4
	v_sub_f32_e32 v4, v18, v33
	v_add_f32_e32 v3, v63, v3
	v_mul_f32_e32 v4, 0x3fb8aa3b, v4
	v_add_f32_e32 v3, v79, v3
	v_exp_f32_e32 v119, v4
	v_sub_f32_e32 v4, v19, v33
	v_add_f32_e32 v3, v102, v3
	v_mul_f32_e32 v4, 0x3fb8aa3b, v4
	v_add_f32_e32 v3, v103, v3
	v_exp_f32_e32 v120, v4
	v_sub_f32_e32 v4, v20, v33
	v_add_f32_e32 v3, v104, v3
	v_mul_f32_e32 v4, 0x3fb8aa3b, v4
	v_add_f32_e32 v3, v105, v3
	v_exp_f32_e32 v121, v4
	v_sub_f32_e32 v4, v21, v33
	v_add_f32_e32 v3, v106, v3
	v_mul_f32_e32 v4, 0x3fb8aa3b, v4
	v_add_f32_e32 v3, v107, v3
	v_exp_f32_e32 v122, v4
	v_sub_f32_e32 v4, v22, v33
	v_add_f32_e32 v3, v108, v3
	v_mul_f32_e32 v4, 0x3fb8aa3b, v4
	v_add_f32_e32 v3, v109, v3
	v_exp_f32_e32 v123, v4
	v_sub_f32_e32 v4, v23, v33
	v_add_f32_e32 v3, v110, v3
	v_mul_f32_e32 v4, 0x3fb8aa3b, v4
	v_add_f32_e32 v3, v111, v3
	v_exp_f32_e32 v124, v4
	v_sub_f32_e32 v4, v24, v33
	v_add_f32_e32 v3, v112, v3
	v_mul_f32_e32 v4, 0x3fb8aa3b, v4
	v_add_f32_e32 v3, v113, v3
	v_exp_f32_e32 v125, v4
	v_sub_f32_e32 v4, v25, v33
	v_add_f32_e32 v3, v114, v3
	v_mul_f32_e32 v4, 0x3fb8aa3b, v4
	v_add_f32_e32 v3, v115, v3
	v_exp_f32_e32 v126, v4
	v_sub_f32_e32 v4, v26, v33
	v_add_f32_e32 v3, v116, v3
	v_mul_f32_e32 v4, 0x3fb8aa3b, v4
	v_add_f32_e32 v3, v117, v3
	v_exp_f32_e32 v127, v4
	v_sub_f32_e32 v4, v27, v33
	v_add_f32_e32 v3, v118, v3
	v_mul_f32_e32 v4, 0x3fb8aa3b, v4
	v_add_f32_e32 v3, v119, v3
	v_exp_f32_e32 v128, v4
	v_sub_f32_e32 v4, v28, v33
	v_add_f32_e32 v3, v120, v3
	v_mul_f32_e32 v4, 0x3fb8aa3b, v4
	v_add_f32_e32 v3, v121, v3
	v_exp_f32_e32 v129, v4
	v_sub_f32_e32 v4, v29, v33
	v_add_f32_e32 v3, v122, v3
	v_mul_f32_e32 v4, 0x3fb8aa3b, v4
	v_add_f32_e32 v3, v123, v3
	v_exp_f32_e32 v130, v4
	v_sub_f32_e32 v4, v30, v33
	v_add_f32_e32 v3, v124, v3
	v_mul_f32_e32 v4, 0x3fb8aa3b, v4
	v_add_f32_e32 v3, v125, v3
	v_exp_f32_e32 v131, v4
	v_sub_f32_e32 v4, v31, v33
	v_add_f32_e32 v3, v126, v3
	v_mul_f32_e32 v4, 0x3fb8aa3b, v4
	v_sub_f32_e32 v1, v1, v33
	v_add_f32_e32 v3, v127, v3
	v_exp_f32_e32 v132, v4
	v_sub_f32_e32 v4, v100, v33
	v_mul_f32_e32 v1, 0x3fb8aa3b, v1
	v_add_f32_e32 v3, v128, v3
	v_mul_f32_e32 v4, 0x3fb8aa3b, v4
	v_exp_f32_e32 v133, v1
	v_sub_f32_e32 v1, v2, v33
	v_add_f32_e32 v3, v129, v3
	v_exp_f32_e32 v100, v4
	v_mul_f32_e32 v1, 0x3fb8aa3b, v1
	v_add_f32_e32 v3, v130, v3
	v_exp_f32_e32 v134, v1
	v_and_b32_e32 v1, 0xffffffc0, v85
	v_mul_u32_u24_e32 v85, 0x210, v96
	v_add_f32_e32 v3, v131, v3
	v_add3_u32 v1, v86, v1, v85
	v_add_f32_e32 v3, v132, v3
	v_add_u32_e32 v15, 0x9000, v1
	v_add_f32_e32 v14, v100, v3
	ds_read2_b64 v[2:5], v15 offset1:2
	v_add_u32_e32 v54, 0xd000, v1
	v_cvt_pk_bf16_f32 v6, v6, v7
	v_cvt_pk_bf16_f32 v7, v8, v9
	v_cvt_pk_bf16_f32 v8, v10, v11
	v_cvt_pk_bf16_f32 v9, v12, v13
	ds_read2_b64 v[10:13], v54 offset0:64 offset1:66
	ds_read2_b64 v[46:49], v15 offset0:4 offset1:6
	s_waitcnt lgkmcnt(2)
	v_mfma_f32_32x32x16_bf16 v[16:31], v[2:5], v[6:9], 0
	v_sub_f32_e32 v0, v0, v33
	v_mul_f32_e32 v0, 0x3fb8aa3b, v0
	v_exp_f32_e32 v96, v0
	v_sub_f32_e32 v0, v101, v33
	v_mul_f32_e32 v0, 0x3fb8aa3b, v0
	v_sub_f32_e32 v44, v44, v33
	v_add_f32_e32 v14, v133, v14
	v_exp_f32_e32 v101, v0
	ds_read2_b64 v[54:57], v54 offset0:68 offset1:70
	v_mul_f32_e32 v44, 0x3fb8aa3b, v44
	v_add_f32_e32 v45, v134, v14
	s_waitcnt lgkmcnt(2)
	v_mfma_f32_32x32x16_bf16 v[0:15], v[10:13], v[6:9], 0
	v_cvt_pk_bf16_f32 v50, v64, v65
	v_exp_f32_e32 v64, v44
	v_lshlrev_b32_e32 v44, 6, v95
	v_add3_u32 v65, v86, v44, v85
	v_add_f32_e32 v45, v96, v45
	v_cvt_pk_bf16_f32 v51, v66, v67
	v_cvt_pk_bf16_f32 v52, v68, v69
	v_cvt_pk_bf16_f32 v53, v70, v71
	v_add_u32_e32 v66, 0x9000, v65
	v_add_f32_e32 v135, v101, v45
	s_waitcnt lgkmcnt(1)
	v_mfma_f32_32x32x16_bf16 v[16:31], v[46:49], v[50:53], v[16:31]
	ds_read2_b64 v[44:47], v66 offset1:2
	v_sub_f32_e32 v42, v42, v33
	v_mul_f32_e32 v42, 0x3fb8aa3b, v42
	v_cvt_pk_bf16_f32 v48, v72, v73
	v_cvt_pk_bf16_f32 v49, v74, v75
	v_sub_f32_e32 v41, v41, v33
	v_mul_f32_e32 v41, 0x3fb8aa3b, v41
	s_waitcnt lgkmcnt(1)
	v_mfma_f32_32x32x16_bf16 v[0:15], v[54:57], v[50:53], v[0:15]
	v_add_u32_e32 v57, 0xd000, v65
	ds_read2_b64 v[52:55], v57 offset0:64 offset1:66
	v_exp_f32_e32 v65, v42
	v_sub_f32_e32 v42, v43, v33
	v_cvt_pk_bf16_f32 v50, v76, v77
	v_cvt_pk_bf16_f32 v51, v78, v97
	v_mul_f32_e32 v42, 0x3fb8aa3b, v42
	v_exp_f32_e32 v67, v42
	s_waitcnt lgkmcnt(1)
	v_mfma_f32_32x32x16_bf16 v[16:31], v[44:47], v[48:51], v[16:31]
	ds_read2_b64 v[42:45], v66 offset0:4 offset1:6
	v_add_f32_e32 v56, v64, v135
	v_add_f32_e32 v46, v65, v56
	v_cvt_pk_bf16_f32 v47, v58, v59
	v_sub_f32_e32 v39, v39, v33
	v_mul_f32_e32 v39, 0x3fb8aa3b, v39
	v_exp_f32_e32 v58, v39
	s_waitcnt lgkmcnt(1)
	v_mfma_f32_32x32x16_bf16 v[0:15], v[52:55], v[48:51], v[0:15]
	ds_read2_b64 v[50:53], v57 offset0:68 offset1:70
	v_exp_f32_e32 v55, v41
	v_lshlrev_b32_e32 v41, 6, v94
	v_add3_u32 v41, v86, v41, v85
	v_add_f32_e32 v54, v67, v46
	v_cvt_pk_bf16_f32 v46, v98, v99
	v_cvt_pk_bf16_f32 v48, v60, v61
	v_cvt_pk_bf16_f32 v49, v62, v63
	v_add_u32_e32 v56, 0x9000, v41
	v_add_u32_e32 v57, 0xd000, v41
	s_waitcnt lgkmcnt(1)
	v_mfma_f32_32x32x16_bf16 v[16:31], v[42:45], v[46:49], v[16:31]
	ds_read2_b64 v[42:45], v56 offset1:2
	v_sub_f32_e32 v39, v40, v33
	v_mul_f32_e32 v39, 0x3fb8aa3b, v39
	v_sub_f32_e32 v38, v38, v33
	v_exp_f32_e32 v59, v39
	v_mul_f32_e32 v38, 0x3fb8aa3b, v38
	v_add_f32_e32 v54, v55, v54
	s_waitcnt lgkmcnt(1)
	v_mfma_f32_32x32x16_bf16 v[0:15], v[50:53], v[46:49], v[0:15]
	ds_read2_b64 v[50:53], v57 offset0:64 offset1:66
	v_cvt_pk_bf16_f32 v46, v79, v102
	v_cvt_pk_bf16_f32 v47, v103, v104
	v_cvt_pk_bf16_f32 v48, v105, v106
	v_cvt_pk_bf16_f32 v49, v107, v108
	v_add_f32_e32 v39, v58, v54
	v_sub_f32_e32 v35, v35, v33
	s_waitcnt lgkmcnt(1)
	v_mfma_f32_32x32x16_bf16 v[16:31], v[42:45], v[46:49], v[16:31]
	ds_read2_b64 v[40:43], v56 offset0:4 offset1:6
	v_cvt_pk_bf16_f32 v44, v109, v110
	v_cvt_pk_bf16_f32 v45, v111, v112
	v_mul_f32_e32 v35, 0x3fb8aa3b, v35
	v_sub_f32_e32 v34, v34, v33
	s_waitcnt lgkmcnt(1)
	v_mfma_f32_32x32x16_bf16 v[0:15], v[50:53], v[46:49], v[0:15]
	v_exp_f32_e32 v53, v38
	v_lshlrev_b32_e32 v38, 6, v93
	ds_read2_b64 v[48:51], v57 offset0:68 offset1:70
	v_add3_u32 v54, v86, v38, v85
	v_cvt_pk_bf16_f32 v46, v113, v114
	v_cvt_pk_bf16_f32 v47, v115, v116
	v_add_u32_e32 v56, 0x9000, v54
	v_add_f32_e32 v52, v59, v39
	s_waitcnt lgkmcnt(1)
	v_mfma_f32_32x32x16_bf16 v[16:31], v[40:43], v[44:47], v[16:31]
	ds_read2_b64 v[38:41], v56 offset1:2
	v_cvt_pk_bf16_f32 v42, v117, v118
	v_cvt_pk_bf16_f32 v43, v119, v120
	s_waitcnt lgkmcnt(1)
	v_mfma_f32_32x32x16_bf16 v[0:15], v[48:51], v[44:47], v[0:15]
	v_add_u32_e32 v51, 0xd000, v54
	v_cvt_pk_bf16_f32 v44, v121, v122
	v_cvt_pk_bf16_f32 v45, v123, v124
	ds_read2_b64 v[46:49], v51 offset0:64 offset1:66
	v_add_f32_e32 v50, v53, v52
	v_exp_f32_e32 v52, v35
	v_sub_f32_e32 v35, v37, v33
	s_waitcnt lgkmcnt(1)
	v_mfma_f32_32x32x16_bf16 v[16:31], v[38:41], v[42:45], v[16:31]
	ds_read2_b64 v[38:41], v56 offset0:4 offset1:6
	v_mul_f32_e32 v35, 0x3fb8aa3b, v35
	v_exp_f32_e32 v54, v35
	v_sub_f32_e32 v35, v36, v33
	v_mul_f32_e32 v35, 0x3fb8aa3b, v35
	s_waitcnt lgkmcnt(1)
	v_mfma_f32_32x32x16_bf16 v[0:15], v[46:49], v[42:45], v[0:15]
	v_cvt_pk_bf16_f32 v42, v125, v126
	v_cvt_pk_bf16_f32 v43, v127, v128
	v_cvt_pk_bf16_f32 v44, v129, v130
	v_cvt_pk_bf16_f32 v45, v131, v132
	ds_read2_b64 v[46:49], v51 offset0:68 offset1:70
	v_exp_f32_e32 v51, v35
	s_waitcnt lgkmcnt(1)
	v_mfma_f32_32x32x16_bf16 v[16:31], v[38:41], v[42:45], v[16:31]
	v_mul_f32_e32 v38, 0x3fb8aa3b, v34
	v_lshlrev_b32_e32 v34, 6, v92
	v_add3_u32 v56, v86, v34, v85
	v_add_u32_e32 v57, 0x9000, v56
	ds_read2_b64 v[34:37], v57 offset1:2
	v_cvt_pk_bf16_f32 v39, v134, v96
	v_cvt_pk_bf16_f32 v40, v101, v64
	s_waitcnt lgkmcnt(1)
	v_mfma_f32_32x32x16_bf16 v[0:15], v[46:49], v[42:45], v[0:15]
	v_exp_f32_e32 v46, v38
	v_cvt_pk_bf16_f32 v38, v100, v133
	v_cvt_pk_bf16_f32 v41, v65, v67
	v_add_u32_e32 v47, 0xd000, v56
	ds_read2_b64 v[42:45], v47 offset0:64 offset1:66
	v_ashrrev_i32_e32 v85, 31, v84
	s_waitcnt lgkmcnt(1)
	v_mfma_f32_32x32x16_bf16 v[16:31], v[34:37], v[38:41], v[16:31]
	v_add_f32_e32 v34, v52, v50
	v_add_f32_e32 v34, v54, v34
	v_add_f32_e32 v34, v51, v34
	v_add_f32_e32 v48, v46, v34
	ds_bpermute_b32 v49, v32, v48
	v_sub_f32_e32 v36, v87, v33
	ds_read2_b64 v[32:35], v57 offset0:4 offset1:6
	v_mul_f32_e32 v36, 0x3fb8aa3b, v36
	s_waitcnt lgkmcnt(2)
	v_mfma_f32_32x32x16_bf16 v[0:15], v[42:45], v[38:41], v[0:15]
	v_exp_f32_e32 v44, v36
	ds_read2_b64 v[40:43], v47 offset0:68 offset1:70
	v_cvt_pk_bf16_f32 v36, v55, v58
	v_cvt_pk_bf16_f32 v37, v59, v53
	v_cvt_pk_bf16_f32 v38, v52, v54
	v_cvt_pk_bf16_f32 v39, v51, v46
	s_waitcnt lgkmcnt(1)
	s_nop 0
	v_mfma_f32_32x32x16_bf16 v[16:31], v[32:35], v[36:39], v[16:31]
	v_add_f32_e32 v32, v48, v49
	v_add_f32_e32 v32, v44, v32
	v_div_scale_f32 v33, s[4:5], v32, v32, 1.0
	v_rcp_f32_e32 v34, v33
	s_nop 0
	v_fma_f32 v35, -v33, v34, 1.0
	s_waitcnt lgkmcnt(0)
	v_mfma_f32_32x32x16_bf16 v[0:15], v[40:43], v[36:39], v[0:15]
	v_fmac_f32_e32 v34, v35, v34
	v_div_scale_f32 v35, vcc, 1.0, v32, 1.0
	v_mul_f32_e32 v36, v35, v34
	v_fma_f32 v37, -v33, v36, v35
	v_fmac_f32_e32 v36, v37, v34
	v_fma_f32 v33, -v33, v36, v35
	v_div_fmas_f32 v33, v33, v34, v36
	v_lshlrev_b64 v[34:35], 11, v[84:85]
	v_div_fixup_f32 v32, v33, v32, 1.0
	v_lshl_add_u64 v[34:35], s[46:47], 0, v[34:35]
	v_lshl_add_u64 v[34:35], v[34:35], 0, s[16:17]
	v_pk_mul_f32 v[16:17], v[16:17], v[32:33] op_sel_hi:[1,0]
	v_pk_mul_f32 v[18:19], v[18:19], v[32:33] op_sel_hi:[1,0]
	v_pk_mul_f32 v[0:1], v[0:1], v[32:33] op_sel_hi:[1,0]
	v_pk_mul_f32 v[2:3], v[2:3], v[32:33] op_sel_hi:[1,0]
	v_lshl_add_u64 v[34:35], v[34:35], 0, v[80:81]
	v_cvt_pk_bf16_f32 v16, v16, v17
	v_cvt_pk_bf16_f32 v17, v18, v19
	v_cvt_pk_bf16_f32 v0, v0, v1
	v_cvt_pk_bf16_f32 v1, v2, v3
	global_store_dwordx2 v[34:35], v[16:17], off
	v_pk_mul_f32 v[16:17], v[20:21], v[32:33] op_sel_hi:[1,0]
	v_pk_mul_f32 v[18:19], v[22:23], v[32:33] op_sel_hi:[1,0]
	global_store_dwordx2 v[34:35], v[0:1], off offset:64
	v_pk_mul_f32 v[0:1], v[4:5], v[32:33] op_sel_hi:[1,0]
	v_pk_mul_f32 v[2:3], v[6:7], v[32:33] op_sel_hi:[1,0]
	v_cvt_pk_bf16_f32 v16, v16, v17
	v_cvt_pk_bf16_f32 v17, v18, v19
	v_cvt_pk_bf16_f32 v0, v0, v1
	v_cvt_pk_bf16_f32 v1, v2, v3
	global_store_dwordx2 v[34:35], v[16:17], off offset:16
	v_pk_mul_f32 v[16:17], v[24:25], v[32:33] op_sel_hi:[1,0]
	v_pk_mul_f32 v[18:19], v[26:27], v[32:33] op_sel_hi:[1,0]
	global_store_dwordx2 v[34:35], v[0:1], off offset:80
	v_pk_mul_f32 v[0:1], v[8:9], v[32:33] op_sel_hi:[1,0]
	v_pk_mul_f32 v[2:3], v[10:11], v[32:33] op_sel_hi:[1,0]
	v_cvt_pk_bf16_f32 v16, v16, v17
	v_cvt_pk_bf16_f32 v17, v18, v19
	v_cvt_pk_bf16_f32 v0, v0, v1
	v_cvt_pk_bf16_f32 v1, v2, v3
	global_store_dwordx2 v[34:35], v[16:17], off offset:32
	v_pk_mul_f32 v[16:17], v[28:29], v[32:33] op_sel_hi:[1,0]
	v_pk_mul_f32 v[18:19], v[30:31], v[32:33] op_sel_hi:[1,0]
	global_store_dwordx2 v[34:35], v[0:1], off offset:96
	v_pk_mul_f32 v[0:1], v[12:13], v[32:33] op_sel_hi:[1,0]
	v_pk_mul_f32 v[2:3], v[14:15], v[32:33] op_sel_hi:[1,0]
	v_cvt_pk_bf16_f32 v16, v16, v17
	v_cvt_pk_bf16_f32 v17, v18, v19
	v_cvt_pk_bf16_f32 v0, v0, v1
	v_cvt_pk_bf16_f32 v1, v2, v3
	global_store_dwordx2 v[34:35], v[16:17], off offset:48
	global_store_dwordx2 v[34:35], v[0:1], off offset:112
	s_cbranch_scc0 .LBB0_781
.LBB0_765:
	s_and_b32 s99, s53, 7
	s_cmp_eq_u32 s99, 0
	s_cselect_b64 s[100:101], -1, 0
	s_bfe_u32 s6, s53, 0x70004
	s_lshl_b32 s8, s6, 7
	v_mov_b32_e32 v85, v205
	s_add_i32 s10, s8, 0xffffff80
	v_and_b32_e32 v10, 7, v85
	v_ashrrev_i32_e32 v1, 3, v85
	s_lshl_b32 s4, s53, 3
	v_lshlrev_b32_e32 v2, 3, v10
	v_add_u32_e32 v11, s10, v1
	s_and_b32 s7, s38, 0xffffc000
	s_and_b32 s9, s4, 64
	v_cmp_lt_i32_e32 vcc, -1, v11
	v_mov_b32_e32 v0, 0
	v_lshlrev_b32_e32 v80, 1, v2
	v_mov_b32_e32 v6, 0
	v_mov_b32_e32 v7, 0
	v_mov_b32_e32 v8, 0
	v_mov_b32_e32 v9, 0
	v_mov_b32_e32 v2, 0
	v_mov_b32_e32 v3, 0
	v_mov_b32_e32 v4, 0
	v_mov_b32_e32 v5, 0
	s_barrier
	s_and_b64 vcc, vcc, s[100:101]
	s_and_saveexec_b64 s[4:5], vcc
	s_cbranch_execz .LBB0_767
	v_add_u32_e32 v4, s7, v11
	v_mov_b64_e32 v[2:3], s[44:45]
	v_mad_i64_i32 v[2:3], s[12:13], v4, s40, v[2:3]
	s_lshl_b32 s16, s9, 1
	v_lshl_add_u64 v[2:3], v[2:3], 0, s[16:17]
	v_lshl_add_u64 v[2:3], v[2:3], 0, v[80:81]
	global_load_dwordx4 v[6:9], v[2:3], off offset:2048
	s_nop 0
	global_load_dwordx4 v[2:5], v[2:3], off offset:2304
.LBB0_767:
	s_or_b64 exec, exec, s[4:5]
	v_lshlrev_b32_e32 v12, 4, v10
	v_mad_u32_u24 v13, v10, s41, v12
	v_mad_u64_u32 v[10:11], s[4:5], v1, s50, v[12:13]
	v_lshl_add_u32 v1, v1, 1, v13
	s_mov_b64 vcc, s[100:101]
	s_cbranch_vccz .Lp15_sk2
	s_waitcnt vmcnt(1)
	ds_write_b128 v10, v[6:9]
	s_waitcnt vmcnt(0)
	ds_write_b16 v1, v2 offset:36864
	ds_write_b16_d16_hi v1, v2 offset:37392
	ds_write_b16 v1, v3 offset:37920
	ds_write_b16_d16_hi v1, v3 offset:38448
	ds_write_b16 v1, v4 offset:38976
	ds_write_b16_d16_hi v1, v4 offset:39504
	ds_write_b16 v1, v5 offset:40032
	ds_write_b16_d16_hi v1, v5 offset:40560
.Lp15_sk2:
	v_add_u32_e32 v1, 0x100, v85
	v_ashrrev_i32_e32 v1, 3, v1
	v_add_u32_e32 v10, s10, v1
	v_cmp_lt_i32_e32 vcc, -1, v10
	v_mov_b32_e32 v6, 0
	v_mov_b32_e32 v7, 0
	v_mov_b32_e32 v8, 0
	v_mov_b32_e32 v9, 0
	v_mov_b32_e32 v2, 0
	v_mov_b32_e32 v3, 0
	v_mov_b32_e32 v4, 0
	v_mov_b32_e32 v5, 0
	s_and_b64 vcc, vcc, s[100:101]
	s_and_saveexec_b64 s[4:5], vcc
	s_cbranch_execz .LBB0_769
	v_add_u32_e32 v4, s7, v10
	v_mov_b64_e32 v[2:3], s[44:45]
	v_mad_i64_i32 v[2:3], s[12:13], v4, s40, v[2:3]
	s_lshl_b32 s16, s9, 1
	v_lshl_add_u64 v[2:3], v[2:3], 0, s[16:17]
	v_lshl_add_u64 v[2:3], v[2:3], 0, v[80:81]
	global_load_dwordx4 v[6:9], v[2:3], off offset:2048
	s_nop 0
	global_load_dwordx4 v[2:5], v[2:3], off offset:2304
.LBB0_769:
	s_or_b64 exec, exec, s[4:5]
	v_mad_u64_u32 v[10:11], s[4:5], v1, s50, v[12:13]
	v_lshl_add_u32 v1, v1, 1, v13
	s_mov_b64 vcc, s[100:101]
	s_cbranch_vccz .Lp15_sk3
	s_waitcnt vmcnt(1)
	ds_write_b128 v10, v[6:9]
	s_waitcnt vmcnt(0)
	ds_write_b16 v1, v2 offset:36864
	ds_write_b16_d16_hi v1, v2 offset:37392
	ds_write_b16 v1, v3 offset:37920
	ds_write_b16_d16_hi v1, v3 offset:38448
	ds_write_b16 v1, v4 offset:38976
	ds_write_b16_d16_hi v1, v4 offset:39504
	ds_write_b16 v1, v5 offset:40032
	ds_write_b16_d16_hi v1, v5 offset:40560
.Lp15_sk3:
	v_add_u32_e32 v1, 0x200, v85
	v_ashrrev_i32_e32 v5, 3, v1
	v_add_u32_e32 v10, s10, v5
	v_cmp_lt_i32_e32 vcc, -1, v10
	v_mov_b32_e32 v4, 0
	v_mov_b32_e32 v1, 0
	v_mov_b32_e32 v2, 0
	v_mov_b32_e32 v3, 0
	v_mov_b32_e32 v6, 0
	v_mov_b32_e32 v7, 0
	v_mov_b32_e32 v8, 0
	v_mov_b32_e32 v9, 0
	s_and_b64 vcc, vcc, s[100:101]
	s_and_saveexec_b64 s[4:5], vcc
	s_cbranch_execz .LBB0_771
	v_add_u32_e32 v2, s7, v10
	v_mov_b64_e32 v[0:1], s[44:45]
	v_mad_i64_i32 v[0:1], s[12:13], v2, s40, v[0:1]
	s_lshl_b32 s16, s9, 1
	v_lshl_add_u64 v[0:1], v[0:1], 0, s[16:17]
	v_lshl_add_u64 v[6:7], v[0:1], 0, v[80:81]
	global_load_dwordx4 v[0:3], v[6:7], off offset:2048
	s_nop 0
	global_load_dwordx4 v[6:9], v[6:7], off offset:2304
.LBB0_771:
	s_or_b64 exec, exec, s[4:5]
	v_mad_u64_u32 v[10:11], s[4:5], v5, s50, v[12:13]
	s_mov_b64 vcc, s[100:101]
	s_cbranch_vccz .Lp15_sk4
	s_waitcnt vmcnt(1)
	ds_write_b128 v10, v[0:3]
.Lp15_sk4:
	v_lshl_add_u32 v0, v5, 1, v13
	s_mov_b64 vcc, s[100:101]
	s_cbranch_vccz .Lp15_sk5
	s_waitcnt vmcnt(0)
	ds_write_b16 v0, v6 offset:36864
	ds_write_b16_d16_hi v0, v6 offset:37392
	ds_write_b16 v0, v7 offset:37920
	ds_write_b16_d16_hi v0, v7 offset:38448
	ds_write_b16 v0, v8 offset:38976
	ds_write_b16_d16_hi v0, v8 offset:39504
	ds_write_b16 v0, v9 offset:40032
	ds_write_b16_d16_hi v0, v9 offset:40560
.Lp15_sk5:
	v_add_u32_e32 v0, 0x300, v85
	v_ashrrev_i32_e32 v5, 3, v0
	v_add_u32_e32 v10, s10, v5
	v_cmp_lt_i32_e32 vcc, -1, v10
	v_mov_b32_e32 v6, 0
	v_mov_b32_e32 v7, 0
	v_mov_b32_e32 v8, 0
	v_mov_b32_e32 v9, 0
	v_mov_b32_e32 v0, 0
	v_mov_b32_e32 v1, 0
	v_mov_b32_e32 v2, 0
	v_mov_b32_e32 v3, 0
	s_and_b64 vcc, vcc, s[100:101]
	s_and_saveexec_b64 s[4:5], vcc
	s_cbranch_execz .LBB0_773
	v_add_u32_e32 v2, s7, v10
	v_mov_b64_e32 v[0:1], s[44:45]
	v_mad_i64_i32 v[0:1], s[12:13], v2, s40, v[0:1]
	s_lshl_b32 s16, s9, 1
	v_lshl_add_u64 v[0:1], v[0:1], 0, s[16:17]
	v_lshl_add_u64 v[0:1], v[0:1], 0, v[80:81]
	global_load_dwordx4 v[6:9], v[0:1], off offset:2048
	s_nop 0
	global_load_dwordx4 v[0:3], v[0:1], off offset:2304
.LBB0_773:
	s_or_b64 exec, exec, s[4:5]
	v_mad_u64_u32 v[10:11], s[4:5], v5, s50, v[12:13]
	v_lshl_add_u32 v5, v5, 1, v13
	s_mov_b64 vcc, s[100:101]
	s_cbranch_vccz .Lp15_sk6
	s_waitcnt vmcnt(1)
	ds_write_b128 v10, v[6:9]
	s_waitcnt vmcnt(0)
	ds_write_b16 v5, v0 offset:36864
	ds_write_b16_d16_hi v5, v0 offset:37392
	ds_write_b16 v5, v1 offset:37920
	ds_write_b16_d16_hi v5, v1 offset:38448
	ds_write_b16 v5, v2 offset:38976
	ds_write_b16_d16_hi v5, v2 offset:39504
	ds_write_b16 v5, v3 offset:40032
	ds_write_b16_d16_hi v5, v3 offset:40560
.Lp15_sk6:
	v_add_u32_e32 v0, 0x400, v85
	v_ashrrev_i32_e32 v1, 3, v0
	v_add_u32_e32 v2, s10, v1
	v_cmp_lt_i32_e32 vcc, -1, v2
	v_mov_b32_e32 v0, 0
	v_mov_b32_e32 v5, 0
	v_mov_b32_e32 v6, 0
	v_mov_b32_e32 v7, 0
	v_mov_b32_e32 v8, 0
	v_mov_b32_e32 v9, 0
	v_mov_b32_e32 v10, 0
	v_mov_b32_e32 v11, 0
	s_and_b64 vcc, vcc, s[100:101]
	s_and_saveexec_b64 s[4:5], vcc
	s_cbranch_execz .LBB0_775
	v_add_u32_e32 v4, s7, v2
	v_mov_b64_e32 v[2:3], s[44:45]
	v_mad_i64_i32 v[2:3], s[12:13], v4, s40, v[2:3]
	s_lshl_b32 s16, s9, 1
	v_lshl_add_u64 v[2:3], v[2:3], 0, s[16:17]
	v_lshl_add_u64 v[2:3], v[2:3], 0, v[80:81]
	global_load_dwordx4 v[4:7], v[2:3], off offset:2048
	global_load_dwordx4 v[8:11], v[2:3], off offset:2304
.LBB0_775:
	s_or_b64 exec, exec, s[4:5]
	v_mad_u64_u32 v[2:3], s[4:5], v1, s50, v[12:13]
	v_lshl_add_u32 v1, v1, 1, v13
	s_mov_b64 vcc, s[100:101]
	s_cbranch_vccz .Lp15_sk7
	s_waitcnt vmcnt(1)
	ds_write_b128 v2, v[4:7]
	s_waitcnt vmcnt(0)
	ds_write_b16 v1, v8 offset:36864
	ds_write_b16_d16_hi v1, v8 offset:37392
	ds_write_b16 v1, v9 offset:37920
	ds_write_b16_d16_hi v1, v9 offset:38448
	ds_write_b16 v1, v10 offset:38976
	ds_write_b16_d16_hi v1, v10 offset:39504
	ds_write_b16 v1, v11 offset:40032
	ds_write_b16_d16_hi v1, v11 offset:40560
.Lp15_sk7:
	v_add_u32_e32 v1, 0x500, v85
	v_ashrrev_i32_e32 v1, 3, v1
	v_add_u32_e32 v10, s10, v1
	v_cmp_lt_i32_e32 vcc, -1, v10
	v_mov_b32_e32 v6, 0
	v_mov_b32_e32 v7, 0
	v_mov_b32_e32 v8, 0
	v_mov_b32_e32 v9, 0
	v_mov_b32_e32 v2, 0
	v_mov_b32_e32 v3, 0
	v_mov_b32_e32 v4, 0
	v_mov_b32_e32 v5, 0
	s_and_b64 vcc, vcc, s[100:101]
	s_and_saveexec_b64 s[4:5], vcc
	s_cbranch_execz .LBB0_777
	v_add_u32_e32 v4, s7, v10
	v_mov_b64_e32 v[2:3], s[44:45]
	v_mad_i64_i32 v[2:3], s[12:13], v4, s40, v[2:3]
	s_lshl_b32 s16, s9, 1
	v_lshl_add_u64 v[2:3], v[2:3], 0, s[16:17]
	v_lshl_add_u64 v[2:3], v[2:3], 0, v[80:81]
	global_load_dwordx4 v[6:9], v[2:3], off offset:2048
	s_nop 0
	global_load_dwordx4 v[2:5], v[2:3], off offset:2304

.Lp15_sk8:
	v_add_u32_e32 v1, 0x600, v85
	v_ashrrev_i32_e32 v5, 3, v1
	v_add_u32_e32 v10, s10, v5
	v_cmp_lt_i32_e32 vcc, -1, v10
	v_mov_b32_e32 v4, 0
	v_mov_b32_e32 v1, 0
	v_mov_b32_e32 v2, 0
	v_mov_b32_e32 v3, 0
	v_mov_b32_e32 v6, 0
	v_mov_b32_e32 v7, 0
	v_mov_b32_e32 v8, 0
	v_mov_b32_e32 v9, 0
	s_and_b64 vcc, vcc, s[100:101]
	s_and_saveexec_b64 s[4:5], vcc
	s_cbranch_execz .LBB0_779
	v_add_u32_e32 v2, s7, v10
	v_mov_b64_e32 v[0:1], s[44:45]
	v_mad_i64_i32 v[0:1], s[12:13], v2, s40, v[0:1]
	s_lshl_b32 s16, s9, 1
	v_lshl_add_u64 v[0:1], v[0:1], 0, s[16:17]
	v_lshl_add_u64 v[6:7], v[0:1], 0, v[80:81]
	global_load_dwordx4 v[0:3], v[6:7], off offset:2048
	s_nop 0
	global_load_dwordx4 v[6:9], v[6:7], off offset:2304

.Lp15_sk10:
	v_add_u32_e32 v0, 0x700, v85
	v_ashrrev_i32_e32 v8, 3, v0
	v_add_u32_e32 v9, s10, v8
	v_cmp_lt_i32_e32 vcc, -1, v9
	v_mov_b32_e32 v5, 0
	v_mov_b32_e32 v6, 0
	v_mov_b32_e32 v7, 0
	v_mov_b32_e32 v0, 0
	v_mov_b32_e32 v1, 0
	v_mov_b32_e32 v2, 0
	v_mov_b32_e32 v3, 0
	s_and_b64 vcc, vcc, s[100:101]
	s_and_saveexec_b64 s[4:5], vcc
	s_cbranch_execz .LBB0_764
	v_add_u32_e32 v2, s7, v9
	v_mov_b64_e32 v[0:1], s[44:45]
	v_mad_i64_i32 v[0:1], s[10:11], v2, s40, v[0:1]
	s_lshl_b32 s16, s9, 1
	v_lshl_add_u64 v[0:1], v[0:1], 0, s[16:17]
	v_lshl_add_u64 v[0:1], v[0:1], 0, v[80:81]
	global_load_dwordx4 v[4:7], v[0:1], off offset:2048
	s_nop 0
	global_load_dwordx4 v[0:3], v[0:1], off offset:2304
	s_branch .LBB0_764
